# speedup vs baseline: 1.0411x; 1.0113x over previous
; #define LAS __attribute__((address_space(3)))
; __device__ __forceinline__ unsigned cvt_pk_bf16(float lo, float hi) { return __builtin_bit_cast(unsigned, __builtin_amdgcn_cvt_pkrtz(lo, hi)); }
; #define bx (opaque_bx())
; __device__ __forceinline__ void phase_prep(int wid_s, const Args& a, unsigned char* shm) {
;     ...
;         while (t < PT_TOTAL) {
;             { const int w = tid >> 6, s4 = tid & 63;
; #pragma unroll
;               for (int q = 0; q < 4; ++q) { const u32x4 pc = {cvt_pk_bf16(r[0][q], r[1][q]), cvt_pk_bf16(r[2][q], r[3][q]), cvt_pk_bf16(r[4][q], r[5][q]), cvt_pk_bf16(r[6][q], r[7][q])};
;                   *(LAS u32x4*)(Lp + (4 * s4 + q) * 36 + 4 * w) = pc; } }
;             __syncthreads();
;             const PrepTask C = T; ++j; const int tn = ((j >> 2) * G + bx) * 4 + (j & 3);
;             if (tn < PT_TOTAL) { T = prep_decode(a, tn); prep_load(T, r, tid); }
.LBB0_42:
	s_lshr_b32 s9, s37, 2
	s_mul_i32 s9, s9, s76
	v_readlane_b32 s12, v253, 0
	s_add_i32 s9, s9, s12
	s_cmpk_lt_u32 s9, 0x29c
	s_cbranch_scc1 .Lrm_done
	s_sub_u32 s98, s9, 0x29c
	s_movk_i32 s99, 0x29c
	s_cmpk_lt_u32 s98, 188
	s_cbranch_scc1 .Lrm_q
	s_sub_u32 s98, s98, 188
	s_addk_i32 s99, 0x29c
	s_cmpk_lt_u32 s98, 188
	s_cbranch_scc1 .Lrm_q
	s_sub_u32 s98, s98, 188
	s_addk_i32 s99, 0x29c
	s_cmpk_lt_u32 s98, 188
	s_cbranch_scc1 .Lrm_q
	s_sub_u32 s98, s98, 188
	s_addk_i32 s99, 0x29c
.Lrm_q:
	s_cmpk_lt_u32 s98, 0x90
	s_cbranch_scc1 .Lrm_add
	s_addk_i32 s98, 0x140
	s_cmpk_lt_u32 s98, 0x1e8
	s_cbranch_scc1 .Lrm_add
	s_addk_i32 s98, 0xa0

; __host__ __device__ __forceinline__ int in_logical_pn(int j) { return (j < 6) ? j : (j < 8 ? j + 2 : j - 2); }
; #define ws (opaque_base(a.ws))
; __device__ __forceinline__ PrepTask prep_decode(const Args& a, int t) {
;     ...
;     else if ((r -= PT_UP) < PT_DN) { T.src = a.w_down + (size_t)l * DFF * DM; T.dst = (bf16_t*)(a.ws + WS_WDN + l * SZ_WDN); T.K = DFF; T.Nnat = DM; T.kind = KIND_STD; nt = 8; }
;     else { r -= PT_DN; T.src = a.glu_w + (size_t)l * 512 * 1024; T.dst = (bf16_t*)(a.ws + WS_WGLU + l * SZ_WGLU); T.K = 512; T.Nnat = 1024; T.kind = KIND_GLU; nt = 4; }
;     (void)nt; const int KT = T.K / 64; T.pn = r / KT; T.k0 = (r % KT) * 64; return T;
; }
; __device__ __forceinline__ void prep_load(const PrepTask& T, f32x4 (&r)[8], int tid) {
;     const int w = tid >> 6, s4 = tid & 63; const int col = colmap(T.kind, T.kind == KIND_IN ? in_logical_pn(T.pn) : T.pn, 4 * s4);
; #pragma unroll
;     for (int i = 0; i < 8; ++i) r[i] = __builtin_nontemporal_load((const f32x4*)(T.src + (size_t)(T.k0 + 8 * w + i) * T.Nnat + col));
; }
.LBB0_808:
	s_waitcnt vmcnt(0)
	s_barrier
	s_cmp_gt_u32 s86, 2
	s_cbranch_scc1 .Ltp_done
	v_readlane_b32 s5, v253, 0
	s_sub_u32 s5, s5, 0x60
	s_cbranch_scc1 .Ltp_done
	s_cmp_gt_u32 s5, 0x9f
	s_cbranch_scc1 .Ltp_done
	s_mov_b64 exec, -1
	s_mov_b32 s20, s5
	s_lshr_b32 s6, s5, 2
	s_and_b32 s5, s5, 3
	s_add_i32 s7, s86, 1
	s_mul_i32 s8, s7, 0x5600000
	s_mul_i32 s9, s5, 0x1580000
	s_add_u32 s8, s8, s9
	s_lshl_b32 s9, s6, 9
	s_add_u32 s8, s8, s9
	v_readlane_b32 s0, v253, 23
	v_readlane_b32 s1, v253, 24
	s_add_u32 s0, s0, s8
	s_addc_u32 s1, s1, 0
	s_mul_i32 s8, s7, 0x2b00000
	s_add_u32 s8, s8, 0x4800000
	s_lshl_b32 s9, s6, 20
	s_add_u32 s8, s8, s9
	s_lshl_b32 s9, s5, 10
	s_add_u32 s8, s8, s9
	s_add_u32 s2, s72, s8
	s_addc_u32 s3, s73, 0
	v_readlane_b32 s16, v253, 29
	v_readlane_b32 s17, v253, 30
	s_mul_i32 s8, s7, 0x2b00000
	s_add_u32 s16, s16, s8
	s_addc_u32 s17, s17, 0
	s_mul_i32 s8, s7, 0x1580000
	s_add_u32 s8, s8, 0xf400000
	s_add_u32 s18, s72, s8
	s_addc_u32 s19, s73, 0
	v_mbcnt_lo_u32_b32 v114, -1, 0
	v_mbcnt_hi_u32_b32 v114, -1, v114
	v_readlane_b32 s5, v253, 37
	s_lshr_b32 s6, s5, 6
	v_bfe_u32 v115, v114, 5, 1
	v_bfe_u32 v116, v114, 3, 2
	v_and_b32_e32 v117, 3, v114
	v_bfe_u32 v118, v114, 2, 1
	v_lshlrev_b32_e32 v116, 7, v116
	v_lshl_add_u32 v116, v117, 5, v116
	v_lshl_add_u32 v116, v118, 4, v116
	v_mul_u32_u24_e32 v117, 0x5600, v115
	v_add_u32_e32 v117, v117, v116
	s_mul_i32 s7, s6, 0x56000
	v_add_u32_e32 v100, s7, v117
	v_add_u32_e32 v101, 0xac00, v100
	v_add_u32_e32 v102, 0xac00, v101
	v_add_u32_e32 v103, 0xac00, v102
	v_add_u32_e32 v104, 0xac00, v103
	v_add_u32_e32 v105, 0xac00, v104
	v_add_u32_e32 v106, 0xac00, v105
	v_add_u32_e32 v107, 0xac00, v106
	v_lshl_add_u32 v117, v115, 9, v116
	s_lshl_b32 s7, s6, 16
	v_add_u32_e32 v120, s7, v117
	v_add_u32_e32 v121, 0x2000, v120
	v_add_u32_e32 v122, 0x2000, v121
	v_add_u32_e32 v123, 0x2000, v122
	v_add_u32_e32 v124, 0x2000, v123
	v_add_u32_e32 v125, 0x2000, v124
	v_add_u32_e32 v126, 0x2000, v125
	v_add_u32_e32 v127, 0x2000, v126
	v_mul_u32_u24_e32 v108, 0x240, v114
	s_lshl_b32 s7, s6, 4
	v_add_u32_e32 v108, s7, v108
	v_lshrrev_b32_e32 v116, 3, v114
	s_lshl_b32 s7, s6, 3
	v_add_u32_e32 v116, s7, v116
	v_and_b32_e32 v117, 7, v114
	v_lshlrev_b32_e32 v117, 4, v117
	v_mul_u32_u24_e32 v109, 0x90, v116
	v_add_u32_e32 v109, v109, v117
	v_lshl_add_u32 v110, v116, 12, v117
	v_add_u32_e32 v111, 0x40000, v110
	v_add_u32_e32 v112, 0x40000, v111
	v_add_u32_e32 v113, 0x40000, v112
	v_mul_u32_u24_e32 v128, 0x2b00, v116
	v_add_u32_e32 v128, v128, v117
	v_add_u32_e32 v129, 0xac000, v128
	v_add_u32_e32 v130, 0xac000, v129
	v_add_u32_e32 v131, 0xac000, v130
	global_load_dwordx4 v[4:7], v100, s[0:1] nt
	global_load_dwordx4 v[8:11], v101, s[0:1] nt
	global_load_dwordx4 v[12:15], v102, s[0:1] nt
	global_load_dwordx4 v[16:19], v103, s[0:1] nt
	global_load_dwordx4 v[20:23], v104, s[0:1] nt
	global_load_dwordx4 v[24:27], v105, s[0:1] nt
	global_load_dwordx4 v[28:31], v106, s[0:1] nt
	global_load_dwordx4 v[32:35], v107, s[0:1] nt
	s_add_u32 s0, s0, 0x2b0000
	s_addc_u32 s1, s1, 0
	global_load_dwordx4 v[36:39], v100, s[0:1] nt
	global_load_dwordx4 v[40:43], v101, s[0:1] nt
	global_load_dwordx4 v[44:47], v102, s[0:1] nt
	global_load_dwordx4 v[48:51], v103, s[0:1] nt
	global_load_dwordx4 v[52:55], v104, s[0:1] nt
	global_load_dwordx4 v[56:59], v105, s[0:1] nt
	global_load_dwordx4 v[60:63], v106, s[0:1] nt
	global_load_dwordx4 v[64:67], v107, s[0:1] nt
	s_add_u32 s0, s0, 0x2b0000
	s_addc_u32 s1, s1, 0
	s_waitcnt vmcnt(8)
	v_cvt_pkrtz_f16_f32 v68, v4, v8
	v_cvt_pkrtz_f16_f32 v69, v12, v16
	v_cvt_pkrtz_f16_f32 v70, v20, v24
	v_cvt_pkrtz_f16_f32 v71, v28, v32
	ds_write_b128 v108, v[68:71] offset:0
	v_cvt_pkrtz_f16_f32 v72, v5, v9
	v_cvt_pkrtz_f16_f32 v73, v13, v17
	v_cvt_pkrtz_f16_f32 v74, v21, v25
	v_cvt_pkrtz_f16_f32 v75, v29, v33
	ds_write_b128 v108, v[72:75] offset:144
	v_cvt_pkrtz_f16_f32 v76, v6, v10
	v_cvt_pkrtz_f16_f32 v77, v14, v18
	v_cvt_pkrtz_f16_f32 v78, v22, v26
	v_cvt_pkrtz_f16_f32 v79, v30, v34
	ds_write_b128 v108, v[76:79] offset:288
	v_cvt_pkrtz_f16_f32 v80, v7, v11
	v_cvt_pkrtz_f16_f32 v81, v15, v19
	v_cvt_pkrtz_f16_f32 v82, v23, v27
	v_cvt_pkrtz_f16_f32 v83, v31, v35
	ds_write_b128 v108, v[80:83] offset:432
	s_waitcnt lgkmcnt(0)
	s_barrier
	ds_read_b128 v[84:87], v109 offset:0
	ds_read_b128 v[88:91], v109 offset:9216
	ds_read_b128 v[92:95], v109 offset:18432
	ds_read_b128 v[96:99], v109 offset:27648
	s_waitcnt lgkmcnt(3)
	global_store_dwordx4 v110, v[84:87], s[2:3] nt
	s_waitcnt lgkmcnt(2)
	global_store_dwordx4 v111, v[88:91], s[2:3] nt
	s_waitcnt lgkmcnt(1)
	global_store_dwordx4 v112, v[92:95], s[2:3] nt
	s_waitcnt lgkmcnt(0)
	global_store_dwordx4 v113, v[96:99], s[2:3] nt
	s_add_u32 s2, s2, 0x80
	s_addc_u32 s3, s3, 0
	global_load_dwordx4 v[4:7], v100, s[0:1] nt
	global_load_dwordx4 v[8:11], v101, s[0:1] nt
	global_load_dwordx4 v[12:15], v102, s[0:1] nt
	global_load_dwordx4 v[16:19], v103, s[0:1] nt
	global_load_dwordx4 v[20:23], v104, s[0:1] nt
	global_load_dwordx4 v[24:27], v105, s[0:1] nt
	global_load_dwordx4 v[28:31], v106, s[0:1] nt
	global_load_dwordx4 v[32:35], v107, s[0:1] nt
	s_add_u32 s0, s0, 0x2b0000
	s_addc_u32 s1, s1, 0
	s_waitcnt vmcnt(12)
	v_cvt_pkrtz_f16_f32 v68, v36, v40
	v_cvt_pkrtz_f16_f32 v69, v44, v48
	v_cvt_pkrtz_f16_f32 v70, v52, v56
	v_cvt_pkrtz_f16_f32 v71, v60, v64
	ds_write_b128 v108, v[68:71] offset:36864
	v_cvt_pkrtz_f16_f32 v72, v37, v41
	v_cvt_pkrtz_f16_f32 v73, v45, v49
	v_cvt_pkrtz_f16_f32 v74, v53, v57
	v_cvt_pkrtz_f16_f32 v75, v61, v65
	ds_write_b128 v108, v[72:75] offset:37008
	v_cvt_pkrtz_f16_f32 v76, v38, v42
	v_cvt_pkrtz_f16_f32 v77, v46, v50
	v_cvt_pkrtz_f16_f32 v78, v54, v58
	v_cvt_pkrtz_f16_f32 v79, v62, v66
	ds_write_b128 v108, v[76:79] offset:37152
	v_cvt_pkrtz_f16_f32 v80, v39, v43
	v_cvt_pkrtz_f16_f32 v81, v47, v51
	v_cvt_pkrtz_f16_f32 v82, v55, v59
	v_cvt_pkrtz_f16_f32 v83, v63, v67
	ds_write_b128 v108, v[80:83] offset:37296
	s_waitcnt lgkmcnt(0)
	s_barrier
; #define LAS __attribute__((address_space(3)))
; __device__ __forceinline__ unsigned cvt_pk_bf16(float lo, float hi) { return __builtin_bit_cast(unsigned, __builtin_amdgcn_cvt_pkrtz(lo, hi)); }
; #define bx (opaque_bx())
; __device__ __forceinline__ void phase_prep(int wid_s, const Args& a, unsigned char* shm) {
;     ...
;             { const int w = tid >> 6, s4 = tid & 63;
; #pragma unroll
;               for (int q = 0; q < 4; ++q) { const u32x4 pc = {cvt_pk_bf16(r[0][q], r[1][q]), cvt_pk_bf16(r[2][q], r[3][q]), cvt_pk_bf16(r[4][q], r[5][q]), cvt_pk_bf16(r[6][q], r[7][q])};
;                   *(LAS u32x4*)(Lp + (4 * s4 + q) * 36 + 4 * w) = pc; } }
;             __syncthreads();
;             const PrepTask C = T; ++j; const int tn = ((j >> 2) * G + bx) * 4 + (j & 3);
;             if (tn < PT_TOTAL) { T = prep_decode(a, tn); prep_load(T, r, tid); }
; #pragma unroll
;             for (int q = 0; q < 4; ++q) { const int row = q * 64 + (tid >> 3), pc = tid & 7;
;                 const u32x4 v = *(const LAS u32x4*)(Lp + row * 36 + 4 * pc);
;                 *(u32x4*)(C.dst + (size_t)(256 * C.pn + row) * C.K + C.k0 + 8 * pc) = v; }
;             __syncthreads();
;             t = tn;
	ds_read_b128 v[84:87], v109 offset:36864
	ds_read_b128 v[88:91], v109 offset:46080
	ds_read_b128 v[92:95], v109 offset:55296
	ds_read_b128 v[96:99], v109 offset:64512
	s_waitcnt lgkmcnt(3)
	global_store_dwordx4 v110, v[84:87], s[2:3] nt
	s_waitcnt lgkmcnt(2)
	global_store_dwordx4 v111, v[88:91], s[2:3] nt
	s_waitcnt lgkmcnt(1)
	global_store_dwordx4 v112, v[92:95], s[2:3] nt
	s_waitcnt lgkmcnt(0)
	global_store_dwordx4 v113, v[96:99], s[2:3] nt
	s_add_u32 s2, s2, 0x80
	s_addc_u32 s3, s3, 0
	global_load_dwordx4 v[36:39], v100, s[0:1] nt
	global_load_dwordx4 v[40:43], v101, s[0:1] nt
	global_load_dwordx4 v[44:47], v102, s[0:1] nt
	global_load_dwordx4 v[48:51], v103, s[0:1] nt
	global_load_dwordx4 v[52:55], v104, s[0:1] nt
	global_load_dwordx4 v[56:59], v105, s[0:1] nt
	global_load_dwordx4 v[60:63], v106, s[0:1] nt
	global_load_dwordx4 v[64:67], v107, s[0:1] nt
	s_add_u32 s0, s0, 0x2b0000
	s_addc_u32 s1, s1, 0
	s_waitcnt vmcnt(12)
	v_cvt_pkrtz_f16_f32 v68, v4, v8
	v_cvt_pkrtz_f16_f32 v69, v12, v16
	v_cvt_pkrtz_f16_f32 v70, v20, v24
	v_cvt_pkrtz_f16_f32 v71, v28, v32
	ds_write_b128 v108, v[68:71] offset:0
	v_cvt_pkrtz_f16_f32 v72, v5, v9
	v_cvt_pkrtz_f16_f32 v73, v13, v17
	v_cvt_pkrtz_f16_f32 v74, v21, v25
	v_cvt_pkrtz_f16_f32 v75, v29, v33
	ds_write_b128 v108, v[72:75] offset:144
	v_cvt_pkrtz_f16_f32 v76, v6, v10
	v_cvt_pkrtz_f16_f32 v77, v14, v18
	v_cvt_pkrtz_f16_f32 v78, v22, v26
	v_cvt_pkrtz_f16_f32 v79, v30, v34
	ds_write_b128 v108, v[76:79] offset:288
	v_cvt_pkrtz_f16_f32 v80, v7, v11
	v_cvt_pkrtz_f16_f32 v81, v15, v19
	v_cvt_pkrtz_f16_f32 v82, v23, v27
	v_cvt_pkrtz_f16_f32 v83, v31, v35
	ds_write_b128 v108, v[80:83] offset:432
	s_waitcnt lgkmcnt(0)
	s_barrier
	ds_read_b128 v[84:87], v109 offset:0
	ds_read_b128 v[88:91], v109 offset:9216
	ds_read_b128 v[92:95], v109 offset:18432
	ds_read_b128 v[96:99], v109 offset:27648
	s_waitcnt lgkmcnt(3)
	global_store_dwordx4 v110, v[84:87], s[2:3] nt
	s_waitcnt lgkmcnt(2)
	global_store_dwordx4 v111, v[88:91], s[2:3] nt
	s_waitcnt lgkmcnt(1)
	global_store_dwordx4 v112, v[92:95], s[2:3] nt
	s_waitcnt lgkmcnt(0)
	global_store_dwordx4 v113, v[96:99], s[2:3] nt
	s_add_u32 s2, s2, 0x80
	s_addc_u32 s3, s3, 0
	global_load_dwordx4 v[4:7], v100, s[0:1] nt
	global_load_dwordx4 v[8:11], v101, s[0:1] nt
	global_load_dwordx4 v[12:15], v102, s[0:1] nt
	global_load_dwordx4 v[16:19], v103, s[0:1] nt
	global_load_dwordx4 v[20:23], v104, s[0:1] nt
	global_load_dwordx4 v[24:27], v105, s[0:1] nt
	global_load_dwordx4 v[28:31], v106, s[0:1] nt
	global_load_dwordx4 v[32:35], v107, s[0:1] nt
	s_add_u32 s0, s0, 0x2b0000
	s_addc_u32 s1, s1, 0
	s_waitcnt vmcnt(12)
	v_cvt_pkrtz_f16_f32 v68, v36, v40
	v_cvt_pkrtz_f16_f32 v69, v44, v48
	v_cvt_pkrtz_f16_f32 v70, v52, v56
	v_cvt_pkrtz_f16_f32 v71, v60, v64
	ds_write_b128 v108, v[68:71] offset:36864
	v_cvt_pkrtz_f16_f32 v72, v37, v41
	v_cvt_pkrtz_f16_f32 v73, v45, v49
	v_cvt_pkrtz_f16_f32 v74, v53, v57
	v_cvt_pkrtz_f16_f32 v75, v61, v65
	ds_write_b128 v108, v[72:75] offset:37008
	v_cvt_pkrtz_f16_f32 v76, v38, v42
	v_cvt_pkrtz_f16_f32 v77, v46, v50
	v_cvt_pkrtz_f16_f32 v78, v54, v58
	v_cvt_pkrtz_f16_f32 v79, v62, v66
	ds_write_b128 v108, v[76:79] offset:37152
	v_cvt_pkrtz_f16_f32 v80, v39, v43
	v_cvt_pkrtz_f16_f32 v81, v47, v51
	v_cvt_pkrtz_f16_f32 v82, v55, v59
	v_cvt_pkrtz_f16_f32 v83, v63, v67
	ds_write_b128 v108, v[80:83] offset:37296
	s_waitcnt lgkmcnt(0)
	s_barrier
	ds_read_b128 v[84:87], v109 offset:36864
	ds_read_b128 v[88:91], v109 offset:46080
	ds_read_b128 v[92:95], v109 offset:55296
	ds_read_b128 v[96:99], v109 offset:64512
	s_waitcnt lgkmcnt(3)
	global_store_dwordx4 v110, v[84:87], s[2:3] nt
	s_waitcnt lgkmcnt(2)
	global_store_dwordx4 v111, v[88:91], s[2:3] nt
	s_waitcnt lgkmcnt(1)
	global_store_dwordx4 v112, v[92:95], s[2:3] nt
	s_waitcnt lgkmcnt(0)
	global_store_dwordx4 v113, v[96:99], s[2:3] nt
	s_add_u32 s2, s2, 0x80
	s_addc_u32 s3, s3, 0
	global_load_dwordx4 v[36:39], v100, s[0:1] nt
	global_load_dwordx4 v[40:43], v101, s[0:1] nt
	global_load_dwordx4 v[44:47], v102, s[0:1] nt
	global_load_dwordx4 v[48:51], v103, s[0:1] nt
	global_load_dwordx4 v[52:55], v104, s[0:1] nt
	global_load_dwordx4 v[56:59], v105, s[0:1] nt
	global_load_dwordx4 v[60:63], v106, s[0:1] nt
	global_load_dwordx4 v[64:67], v107, s[0:1] nt
	s_add_u32 s0, s0, 0x2b0000
	s_addc_u32 s1, s1, 0
	s_waitcnt vmcnt(12)
	v_cvt_pkrtz_f16_f32 v68, v4, v8
	v_cvt_pkrtz_f16_f32 v69, v12, v16
	v_cvt_pkrtz_f16_f32 v70, v20, v24
	v_cvt_pkrtz_f16_f32 v71, v28, v32
	ds_write_b128 v108, v[68:71] offset:0
	v_cvt_pkrtz_f16_f32 v72, v5, v9
	v_cvt_pkrtz_f16_f32 v73, v13, v17
	v_cvt_pkrtz_f16_f32 v74, v21, v25
	v_cvt_pkrtz_f16_f32 v75, v29, v33
	ds_write_b128 v108, v[72:75] offset:144
	v_cvt_pkrtz_f16_f32 v76, v6, v10
	v_cvt_pkrtz_f16_f32 v77, v14, v18
	v_cvt_pkrtz_f16_f32 v78, v22, v26
	v_cvt_pkrtz_f16_f32 v79, v30, v34
	ds_write_b128 v108, v[76:79] offset:288
	v_cvt_pkrtz_f16_f32 v80, v7, v11
	v_cvt_pkrtz_f16_f32 v81, v15, v19
	v_cvt_pkrtz_f16_f32 v82, v23, v27
	v_cvt_pkrtz_f16_f32 v83, v31, v35
	ds_write_b128 v108, v[80:83] offset:432
	s_waitcnt lgkmcnt(0)
	s_barrier
; #define LAS __attribute__((address_space(3)))
; __device__ __forceinline__ unsigned cvt_pk_bf16(float lo, float hi) { return __builtin_bit_cast(unsigned, __builtin_amdgcn_cvt_pkrtz(lo, hi)); }
; #define bx (opaque_bx())
; #define ws (opaque_base(a.ws))
; __device__ __forceinline__ PrepTask prep_decode(const Args& a, int t) {
;     ...
;     else if ((r -= PT_UP) < PT_DN) { T.src = a.w_down + (size_t)l * DFF * DM; T.dst = (bf16_t*)(a.ws + WS_WDN + l * SZ_WDN); T.K = DFF; T.Nnat = DM; T.kind = KIND_STD; nt = 8; }
;     else { r -= PT_DN; T.src = a.glu_w + (size_t)l * 512 * 1024; T.dst = (bf16_t*)(a.ws + WS_WGLU + l * SZ_WGLU); T.K = 512; T.Nnat = 1024; T.kind = KIND_GLU; nt = 4; }
;     (void)nt; const int KT = T.K / 64; T.pn = r / KT; T.k0 = (r % KT) * 64; return T;
; __device__ __forceinline__ void phase_prep(int wid_s, const Args& a, unsigned char* shm) {
;     ...
;             { const int w = tid >> 6, s4 = tid & 63;
; #pragma unroll
;               for (int q = 0; q < 4; ++q) { const u32x4 pc = {cvt_pk_bf16(r[0][q], r[1][q]), cvt_pk_bf16(r[2][q], r[3][q]), cvt_pk_bf16(r[4][q], r[5][q]), cvt_pk_bf16(r[6][q], r[7][q])};
;                   *(LAS u32x4*)(Lp + (4 * s4 + q) * 36 + 4 * w) = pc; } }
;             __syncthreads();
;             const PrepTask C = T; ++j; const int tn = ((j >> 2) * G + bx) * 4 + (j & 3);
;             if (tn < PT_TOTAL) { T = prep_decode(a, tn); prep_load(T, r, tid); }
; #pragma unroll
;             for (int q = 0; q < 4; ++q) { const int row = q * 64 + (tid >> 3), pc = tid & 7;
;                 const u32x4 v = *(const LAS u32x4*)(Lp + row * 36 + 4 * pc);
;                 *(u32x4*)(C.dst + (size_t)(256 * C.pn + row) * C.K + C.k0 + 8 * pc) = v; }
;             __syncthreads();
;             t = tn;
	ds_read_b128 v[84:87], v109 offset:0
	ds_read_b128 v[88:91], v109 offset:9216
	ds_read_b128 v[92:95], v109 offset:18432
	ds_read_b128 v[96:99], v109 offset:27648
	s_waitcnt lgkmcnt(3)
	global_store_dwordx4 v110, v[84:87], s[2:3] nt
	s_waitcnt lgkmcnt(2)
	global_store_dwordx4 v111, v[88:91], s[2:3] nt
	s_waitcnt lgkmcnt(1)
	global_store_dwordx4 v112, v[92:95], s[2:3] nt
	s_waitcnt lgkmcnt(0)
	global_store_dwordx4 v113, v[96:99], s[2:3] nt
	s_add_u32 s2, s2, 0x80
	s_addc_u32 s3, s3, 0
	global_load_dwordx4 v[4:7], v100, s[0:1] nt
	global_load_dwordx4 v[8:11], v101, s[0:1] nt
	global_load_dwordx4 v[12:15], v102, s[0:1] nt
	global_load_dwordx4 v[16:19], v103, s[0:1] nt
	global_load_dwordx4 v[20:23], v104, s[0:1] nt
	global_load_dwordx4 v[24:27], v105, s[0:1] nt
	global_load_dwordx4 v[28:31], v106, s[0:1] nt
	global_load_dwordx4 v[32:35], v107, s[0:1] nt
	s_add_u32 s0, s0, 0x2b0000
	s_addc_u32 s1, s1, 0
	s_waitcnt vmcnt(12)
	v_cvt_pkrtz_f16_f32 v68, v36, v40
	v_cvt_pkrtz_f16_f32 v69, v44, v48
	v_cvt_pkrtz_f16_f32 v70, v52, v56
	v_cvt_pkrtz_f16_f32 v71, v60, v64
	ds_write_b128 v108, v[68:71] offset:36864
	v_cvt_pkrtz_f16_f32 v72, v37, v41
	v_cvt_pkrtz_f16_f32 v73, v45, v49
	v_cvt_pkrtz_f16_f32 v74, v53, v57
	v_cvt_pkrtz_f16_f32 v75, v61, v65
	ds_write_b128 v108, v[72:75] offset:37008
	v_cvt_pkrtz_f16_f32 v76, v38, v42
	v_cvt_pkrtz_f16_f32 v77, v46, v50
	v_cvt_pkrtz_f16_f32 v78, v54, v58
	v_cvt_pkrtz_f16_f32 v79, v62, v66
	ds_write_b128 v108, v[76:79] offset:37152
	v_cvt_pkrtz_f16_f32 v80, v39, v43
	v_cvt_pkrtz_f16_f32 v81, v47, v51
	v_cvt_pkrtz_f16_f32 v82, v55, v59
	v_cvt_pkrtz_f16_f32 v83, v63, v67
	ds_write_b128 v108, v[80:83] offset:37296
	s_waitcnt lgkmcnt(0)
	s_barrier
	ds_read_b128 v[84:87], v109 offset:36864
	ds_read_b128 v[88:91], v109 offset:46080
	ds_read_b128 v[92:95], v109 offset:55296
	ds_read_b128 v[96:99], v109 offset:64512
	s_waitcnt lgkmcnt(3)
	global_store_dwordx4 v110, v[84:87], s[2:3] nt
	s_waitcnt lgkmcnt(2)
	global_store_dwordx4 v111, v[88:91], s[2:3] nt
	s_waitcnt lgkmcnt(1)
	global_store_dwordx4 v112, v[92:95], s[2:3] nt
	s_waitcnt lgkmcnt(0)
	global_store_dwordx4 v113, v[96:99], s[2:3] nt
	s_add_u32 s2, s2, 0x80
	s_addc_u32 s3, s3, 0
	global_load_dwordx4 v[36:39], v100, s[0:1] nt
	global_load_dwordx4 v[40:43], v101, s[0:1] nt
	global_load_dwordx4 v[44:47], v102, s[0:1] nt
	global_load_dwordx4 v[48:51], v103, s[0:1] nt
	global_load_dwordx4 v[52:55], v104, s[0:1] nt
	global_load_dwordx4 v[56:59], v105, s[0:1] nt
	global_load_dwordx4 v[60:63], v106, s[0:1] nt
	global_load_dwordx4 v[64:67], v107, s[0:1] nt
	s_add_u32 s0, s0, 0x2b0000
	s_addc_u32 s1, s1, 0
	s_waitcnt vmcnt(12)
	v_cvt_pkrtz_f16_f32 v68, v4, v8
	v_cvt_pkrtz_f16_f32 v69, v12, v16
	v_cvt_pkrtz_f16_f32 v70, v20, v24
	v_cvt_pkrtz_f16_f32 v71, v28, v32
	ds_write_b128 v108, v[68:71] offset:0
	v_cvt_pkrtz_f16_f32 v72, v5, v9
	v_cvt_pkrtz_f16_f32 v73, v13, v17
	v_cvt_pkrtz_f16_f32 v74, v21, v25
	v_cvt_pkrtz_f16_f32 v75, v29, v33
	ds_write_b128 v108, v[72:75] offset:144
	v_cvt_pkrtz_f16_f32 v76, v6, v10
	v_cvt_pkrtz_f16_f32 v77, v14, v18
	v_cvt_pkrtz_f16_f32 v78, v22, v26
	v_cvt_pkrtz_f16_f32 v79, v30, v34
	ds_write_b128 v108, v[76:79] offset:288
	v_cvt_pkrtz_f16_f32 v80, v7, v11
	v_cvt_pkrtz_f16_f32 v81, v15, v19
	v_cvt_pkrtz_f16_f32 v82, v23, v27
	v_cvt_pkrtz_f16_f32 v83, v31, v35
	ds_write_b128 v108, v[80:83] offset:432
	s_waitcnt lgkmcnt(0)
	s_barrier
	ds_read_b128 v[84:87], v109 offset:0
	ds_read_b128 v[88:91], v109 offset:9216
	ds_read_b128 v[92:95], v109 offset:18432
	ds_read_b128 v[96:99], v109 offset:27648
	s_waitcnt lgkmcnt(3)
	global_store_dwordx4 v110, v[84:87], s[2:3] nt
	s_waitcnt lgkmcnt(2)
	global_store_dwordx4 v111, v[88:91], s[2:3] nt
	s_waitcnt lgkmcnt(1)
	global_store_dwordx4 v112, v[92:95], s[2:3] nt
	s_waitcnt lgkmcnt(0)
	global_store_dwordx4 v113, v[96:99], s[2:3] nt
	s_add_u32 s2, s2, 0x80
	s_addc_u32 s3, s3, 0
	s_lshl_b32 s8, s20, 2
	s_mul_i32 s9, s8, 0x2fb
	s_lshr_b32 s9, s9, 16
	s_mul_i32 s14, s9, 0x56
	s_sub_u32 s8, s8, s14
	s_lshl_b32 s14, s8, 19
	s_lshl_b32 s15, s9, 10
	s_add_u32 s14, s14, s15
	s_add_u32 s22, s16, s14
	s_addc_u32 s23, s17, 0
	s_mul_i32 s14, s9, 0x2b0000
	s_lshl_b32 s15, s8, 7
	s_add_u32 s14, s14, s15
	s_add_u32 s24, s18, s14
	s_addc_u32 s25, s19, 0
	global_load_dwordx4 v[4:7], v120, s[22:23] nt
	global_load_dwordx4 v[8:11], v121, s[22:23] nt
	global_load_dwordx4 v[12:15], v122, s[22:23] nt
	global_load_dwordx4 v[16:19], v123, s[22:23] nt
	global_load_dwordx4 v[20:23], v124, s[22:23] nt
	global_load_dwordx4 v[24:27], v125, s[22:23] nt
	global_load_dwordx4 v[28:31], v126, s[22:23] nt
	global_load_dwordx4 v[32:35], v127, s[22:23] nt
	s_waitcnt vmcnt(12)
	v_cvt_pkrtz_f16_f32 v68, v36, v40
	v_cvt_pkrtz_f16_f32 v69, v44, v48
	v_cvt_pkrtz_f16_f32 v70, v52, v56
	v_cvt_pkrtz_f16_f32 v71, v60, v64
	ds_write_b128 v108, v[68:71] offset:36864
	v_cvt_pkrtz_f16_f32 v72, v37, v41
	v_cvt_pkrtz_f16_f32 v73, v45, v49
	v_cvt_pkrtz_f16_f32 v74, v53, v57
	v_cvt_pkrtz_f16_f32 v75, v61, v65
	ds_write_b128 v108, v[72:75] offset:37008
	v_cvt_pkrtz_f16_f32 v76, v38, v42
	v_cvt_pkrtz_f16_f32 v77, v46, v50
	v_cvt_pkrtz_f16_f32 v78, v54, v58
	v_cvt_pkrtz_f16_f32 v79, v62, v66
	ds_write_b128 v108, v[76:79] offset:37152
	v_cvt_pkrtz_f16_f32 v80, v39, v43
	v_cvt_pkrtz_f16_f32 v81, v47, v51
	v_cvt_pkrtz_f16_f32 v82, v55, v59
	v_cvt_pkrtz_f16_f32 v83, v63, v67
	ds_write_b128 v108, v[80:83] offset:37296
	s_waitcnt lgkmcnt(0)
	s_barrier
; #define LAS __attribute__((address_space(3)))
; __device__ __forceinline__ unsigned cvt_pk_bf16(float lo, float hi) { return __builtin_bit_cast(unsigned, __builtin_amdgcn_cvt_pkrtz(lo, hi)); }
; #define bx (opaque_bx())
; #define ws (opaque_base(a.ws))
; __device__ __forceinline__ PrepTask prep_decode(const Args& a, int t) {
;     ...
;     else if ((r -= PT_UP) < PT_DN) { T.src = a.w_down + (size_t)l * DFF * DM; T.dst = (bf16_t*)(a.ws + WS_WDN + l * SZ_WDN); T.K = DFF; T.Nnat = DM; T.kind = KIND_STD; nt = 8; }
;     else { r -= PT_DN; T.src = a.glu_w + (size_t)l * 512 * 1024; T.dst = (bf16_t*)(a.ws + WS_WGLU + l * SZ_WGLU); T.K = 512; T.Nnat = 1024; T.kind = KIND_GLU; nt = 4; }
;     (void)nt; const int KT = T.K / 64; T.pn = r / KT; T.k0 = (r % KT) * 64; return T;
; __device__ __forceinline__ void phase_prep(int wid_s, const Args& a, unsigned char* shm) {
;     ...
;             { const int w = tid >> 6, s4 = tid & 63;
; #pragma unroll
;               for (int q = 0; q < 4; ++q) { const u32x4 pc = {cvt_pk_bf16(r[0][q], r[1][q]), cvt_pk_bf16(r[2][q], r[3][q]), cvt_pk_bf16(r[4][q], r[5][q]), cvt_pk_bf16(r[6][q], r[7][q])};
;                   *(LAS u32x4*)(Lp + (4 * s4 + q) * 36 + 4 * w) = pc; } }
;             __syncthreads();
;             const PrepTask C = T; ++j; const int tn = ((j >> 2) * G + bx) * 4 + (j & 3);
;             if (tn < PT_TOTAL) { T = prep_decode(a, tn); prep_load(T, r, tid); }
; #pragma unroll
;             for (int q = 0; q < 4; ++q) { const int row = q * 64 + (tid >> 3), pc = tid & 7;
;                 const u32x4 v = *(const LAS u32x4*)(Lp + row * 36 + 4 * pc);
;                 *(u32x4*)(C.dst + (size_t)(256 * C.pn + row) * C.K + C.k0 + 8 * pc) = v; }
;             __syncthreads();
;             t = tn;
	ds_read_b128 v[84:87], v109 offset:36864
	ds_read_b128 v[88:91], v109 offset:46080
	ds_read_b128 v[92:95], v109 offset:55296
	ds_read_b128 v[96:99], v109 offset:64512
	s_waitcnt lgkmcnt(3)
	global_store_dwordx4 v110, v[84:87], s[2:3] nt
	s_waitcnt lgkmcnt(2)
	global_store_dwordx4 v111, v[88:91], s[2:3] nt
	s_waitcnt lgkmcnt(1)
	global_store_dwordx4 v112, v[92:95], s[2:3] nt
	s_waitcnt lgkmcnt(0)
	global_store_dwordx4 v113, v[96:99], s[2:3] nt
	s_add_u32 s2, s2, 0x80
	s_addc_u32 s3, s3, 0
	s_lshl_b32 s8, s20, 2
	s_add_u32 s8, s8, 1
	s_mul_i32 s9, s8, 0x2fb
	s_lshr_b32 s9, s9, 16
	s_mul_i32 s14, s9, 0x56
	s_sub_u32 s8, s8, s14
	s_lshl_b32 s14, s8, 19
	s_lshl_b32 s15, s9, 10
	s_add_u32 s14, s14, s15
	s_add_u32 s22, s16, s14
	s_addc_u32 s23, s17, 0
	s_mul_i32 s14, s9, 0x2b0000
	s_lshl_b32 s15, s8, 7
	s_add_u32 s14, s14, s15
	s_add_u32 s26, s18, s14
	s_addc_u32 s27, s19, 0
	global_load_dwordx4 v[36:39], v120, s[22:23] nt
	global_load_dwordx4 v[40:43], v121, s[22:23] nt
	global_load_dwordx4 v[44:47], v122, s[22:23] nt
	global_load_dwordx4 v[48:51], v123, s[22:23] nt
	global_load_dwordx4 v[52:55], v124, s[22:23] nt
	global_load_dwordx4 v[56:59], v125, s[22:23] nt
	global_load_dwordx4 v[60:63], v126, s[22:23] nt
	global_load_dwordx4 v[64:67], v127, s[22:23] nt
	s_waitcnt vmcnt(12)
	v_cvt_pkrtz_f16_f32 v68, v4, v8
	v_cvt_pkrtz_f16_f32 v69, v12, v16
	v_cvt_pkrtz_f16_f32 v70, v20, v24
	v_cvt_pkrtz_f16_f32 v71, v28, v32
	ds_write_b128 v108, v[68:71] offset:0
	v_cvt_pkrtz_f16_f32 v72, v5, v9
	v_cvt_pkrtz_f16_f32 v73, v13, v17
	v_cvt_pkrtz_f16_f32 v74, v21, v25
	v_cvt_pkrtz_f16_f32 v75, v29, v33
	ds_write_b128 v108, v[72:75] offset:144
	v_cvt_pkrtz_f16_f32 v76, v6, v10
	v_cvt_pkrtz_f16_f32 v77, v14, v18
	v_cvt_pkrtz_f16_f32 v78, v22, v26
	v_cvt_pkrtz_f16_f32 v79, v30, v34
	ds_write_b128 v108, v[76:79] offset:288
	v_cvt_pkrtz_f16_f32 v80, v7, v11
	v_cvt_pkrtz_f16_f32 v81, v15, v19
	v_cvt_pkrtz_f16_f32 v82, v23, v27
	v_cvt_pkrtz_f16_f32 v83, v31, v35
	ds_write_b128 v108, v[80:83] offset:432
	s_waitcnt lgkmcnt(0)
	s_barrier
	ds_read_b128 v[84:87], v109 offset:0
	ds_read_b128 v[88:91], v109 offset:9216
	ds_read_b128 v[92:95], v109 offset:18432
	ds_read_b128 v[96:99], v109 offset:27648
	s_waitcnt lgkmcnt(3)
	global_store_dwordx4 v128, v[84:87], s[24:25] nt
	s_waitcnt lgkmcnt(2)
	global_store_dwordx4 v129, v[88:91], s[24:25] nt
	s_waitcnt lgkmcnt(1)
	global_store_dwordx4 v130, v[92:95], s[24:25] nt
	s_waitcnt lgkmcnt(0)
	global_store_dwordx4 v131, v[96:99], s[24:25] nt
	s_lshl_b32 s8, s20, 2
	s_add_u32 s8, s8, 2
	s_mul_i32 s9, s8, 0x2fb
	s_lshr_b32 s9, s9, 16
	s_mul_i32 s14, s9, 0x56
	s_sub_u32 s8, s8, s14
	s_lshl_b32 s14, s8, 19
	s_lshl_b32 s15, s9, 10
	s_add_u32 s14, s14, s15
	s_add_u32 s22, s16, s14
	s_addc_u32 s23, s17, 0
	s_mul_i32 s14, s9, 0x2b0000
	s_lshl_b32 s15, s8, 7
	s_add_u32 s14, s14, s15
	s_add_u32 s24, s18, s14
	s_addc_u32 s25, s19, 0
	global_load_dwordx4 v[4:7], v120, s[22:23] nt
	global_load_dwordx4 v[8:11], v121, s[22:23] nt
	global_load_dwordx4 v[12:15], v122, s[22:23] nt
	global_load_dwordx4 v[16:19], v123, s[22:23] nt
	global_load_dwordx4 v[20:23], v124, s[22:23] nt
	global_load_dwordx4 v[24:27], v125, s[22:23] nt
	global_load_dwordx4 v[28:31], v126, s[22:23] nt
	global_load_dwordx4 v[32:35], v127, s[22:23] nt
	s_waitcnt vmcnt(12)
	v_cvt_pkrtz_f16_f32 v68, v36, v40
	v_cvt_pkrtz_f16_f32 v69, v44, v48
	v_cvt_pkrtz_f16_f32 v70, v52, v56
	v_cvt_pkrtz_f16_f32 v71, v60, v64
	ds_write_b128 v108, v[68:71] offset:36864
	v_cvt_pkrtz_f16_f32 v72, v37, v41
	v_cvt_pkrtz_f16_f32 v73, v45, v49
	v_cvt_pkrtz_f16_f32 v74, v53, v57
	v_cvt_pkrtz_f16_f32 v75, v61, v65
	ds_write_b128 v108, v[72:75] offset:37008
	v_cvt_pkrtz_f16_f32 v76, v38, v42
	v_cvt_pkrtz_f16_f32 v77, v46, v50
	v_cvt_pkrtz_f16_f32 v78, v54, v58
	v_cvt_pkrtz_f16_f32 v79, v62, v66
	ds_write_b128 v108, v[76:79] offset:37152
	v_cvt_pkrtz_f16_f32 v80, v39, v43
	v_cvt_pkrtz_f16_f32 v81, v47, v51
	v_cvt_pkrtz_f16_f32 v82, v55, v59
	v_cvt_pkrtz_f16_f32 v83, v63, v67
	ds_write_b128 v108, v[80:83] offset:37296
	s_waitcnt lgkmcnt(0)
	s_barrier
; #define LAS __attribute__((address_space(3)))
; __device__ __forceinline__ unsigned cvt_pk_bf16(float lo, float hi) { return __builtin_bit_cast(unsigned, __builtin_amdgcn_cvt_pkrtz(lo, hi)); }
; #define bx (opaque_bx())
; __device__ __forceinline__ void phase_prep(int wid_s, const Args& a, unsigned char* shm) {
;     ...
;             { const int w = tid >> 6, s4 = tid & 63;
; #pragma unroll
;               for (int q = 0; q < 4; ++q) { const u32x4 pc = {cvt_pk_bf16(r[0][q], r[1][q]), cvt_pk_bf16(r[2][q], r[3][q]), cvt_pk_bf16(r[4][q], r[5][q]), cvt_pk_bf16(r[6][q], r[7][q])};
;                   *(LAS u32x4*)(Lp + (4 * s4 + q) * 36 + 4 * w) = pc; } }
;             __syncthreads();
;             const PrepTask C = T; ++j; const int tn = ((j >> 2) * G + bx) * 4 + (j & 3);
;             if (tn < PT_TOTAL) { T = prep_decode(a, tn); prep_load(T, r, tid); }
; #pragma unroll
;             for (int q = 0; q < 4; ++q) { const int row = q * 64 + (tid >> 3), pc = tid & 7;
;                 const u32x4 v = *(const LAS u32x4*)(Lp + row * 36 + 4 * pc);
;                 *(u32x4*)(C.dst + (size_t)(256 * C.pn + row) * C.K + C.k0 + 8 * pc) = v; }
;             __syncthreads();
;             t = tn;
	ds_read_b128 v[84:87], v109 offset:36864
	ds_read_b128 v[88:91], v109 offset:46080
	ds_read_b128 v[92:95], v109 offset:55296
	ds_read_b128 v[96:99], v109 offset:64512
	s_waitcnt lgkmcnt(3)
	global_store_dwordx4 v128, v[84:87], s[26:27] nt
	s_waitcnt lgkmcnt(2)
	global_store_dwordx4 v129, v[88:91], s[26:27] nt
	s_waitcnt lgkmcnt(1)
	global_store_dwordx4 v130, v[92:95], s[26:27] nt
	s_waitcnt lgkmcnt(0)
	global_store_dwordx4 v131, v[96:99], s[26:27] nt
	s_lshl_b32 s8, s20, 2
	s_add_u32 s8, s8, 3
	s_mul_i32 s9, s8, 0x2fb
	s_lshr_b32 s9, s9, 16
	s_mul_i32 s14, s9, 0x56
	s_sub_u32 s8, s8, s14
	s_lshl_b32 s14, s8, 19
	s_lshl_b32 s15, s9, 10
	s_add_u32 s14, s14, s15
	s_add_u32 s22, s16, s14
	s_addc_u32 s23, s17, 0
	s_mul_i32 s14, s9, 0x2b0000
	s_lshl_b32 s15, s8, 7
	s_add_u32 s14, s14, s15
	s_add_u32 s26, s18, s14
	s_addc_u32 s27, s19, 0
	global_load_dwordx4 v[36:39], v120, s[22:23] nt
	global_load_dwordx4 v[40:43], v121, s[22:23] nt
	global_load_dwordx4 v[44:47], v122, s[22:23] nt
	global_load_dwordx4 v[48:51], v123, s[22:23] nt
	global_load_dwordx4 v[52:55], v124, s[22:23] nt
	global_load_dwordx4 v[56:59], v125, s[22:23] nt
	global_load_dwordx4 v[60:63], v126, s[22:23] nt
	global_load_dwordx4 v[64:67], v127, s[22:23] nt
	s_waitcnt vmcnt(12)
	v_cvt_pkrtz_f16_f32 v68, v4, v8
	v_cvt_pkrtz_f16_f32 v69, v12, v16
	v_cvt_pkrtz_f16_f32 v70, v20, v24
	v_cvt_pkrtz_f16_f32 v71, v28, v32
	ds_write_b128 v108, v[68:71] offset:0
	v_cvt_pkrtz_f16_f32 v72, v5, v9
	v_cvt_pkrtz_f16_f32 v73, v13, v17
	v_cvt_pkrtz_f16_f32 v74, v21, v25
	v_cvt_pkrtz_f16_f32 v75, v29, v33
	ds_write_b128 v108, v[72:75] offset:144
	v_cvt_pkrtz_f16_f32 v76, v6, v10
	v_cvt_pkrtz_f16_f32 v77, v14, v18
	v_cvt_pkrtz_f16_f32 v78, v22, v26
	v_cvt_pkrtz_f16_f32 v79, v30, v34
	ds_write_b128 v108, v[76:79] offset:288
	v_cvt_pkrtz_f16_f32 v80, v7, v11
	v_cvt_pkrtz_f16_f32 v81, v15, v19
	v_cvt_pkrtz_f16_f32 v82, v23, v27
	v_cvt_pkrtz_f16_f32 v83, v31, v35
	ds_write_b128 v108, v[80:83] offset:432
	s_waitcnt lgkmcnt(0)
	s_barrier
	ds_read_b128 v[84:87], v109 offset:0
	ds_read_b128 v[88:91], v109 offset:9216
	ds_read_b128 v[92:95], v109 offset:18432
	ds_read_b128 v[96:99], v109 offset:27648
	s_waitcnt lgkmcnt(3)
	global_store_dwordx4 v128, v[84:87], s[24:25] nt
	s_waitcnt lgkmcnt(2)
	global_store_dwordx4 v129, v[88:91], s[24:25] nt
	s_waitcnt lgkmcnt(1)
	global_store_dwordx4 v130, v[92:95], s[24:25] nt
	s_waitcnt lgkmcnt(0)
	global_store_dwordx4 v131, v[96:99], s[24:25] nt
	s_waitcnt vmcnt(4)
	v_cvt_pkrtz_f16_f32 v68, v36, v40
	v_cvt_pkrtz_f16_f32 v69, v44, v48
	v_cvt_pkrtz_f16_f32 v70, v52, v56
	v_cvt_pkrtz_f16_f32 v71, v60, v64
	ds_write_b128 v108, v[68:71] offset:36864
	v_cvt_pkrtz_f16_f32 v72, v37, v41
	v_cvt_pkrtz_f16_f32 v73, v45, v49
	v_cvt_pkrtz_f16_f32 v74, v53, v57
	v_cvt_pkrtz_f16_f32 v75, v61, v65
	ds_write_b128 v108, v[72:75] offset:37008
	v_cvt_pkrtz_f16_f32 v76, v38, v42
	v_cvt_pkrtz_f16_f32 v77, v46, v50
	v_cvt_pkrtz_f16_f32 v78, v54, v58
	v_cvt_pkrtz_f16_f32 v79, v62, v66
	ds_write_b128 v108, v[76:79] offset:37152
	v_cvt_pkrtz_f16_f32 v80, v39, v43
	v_cvt_pkrtz_f16_f32 v81, v47, v51
	v_cvt_pkrtz_f16_f32 v82, v55, v59
	v_cvt_pkrtz_f16_f32 v83, v63, v67
	ds_write_b128 v108, v[80:83] offset:37296
	s_waitcnt lgkmcnt(0)
	s_barrier
	ds_read_b128 v[84:87], v109 offset:36864
	ds_read_b128 v[88:91], v109 offset:46080
	ds_read_b128 v[92:95], v109 offset:55296
	ds_read_b128 v[96:99], v109 offset:64512
	s_waitcnt lgkmcnt(3)
	global_store_dwordx4 v128, v[84:87], s[26:27] nt
	s_waitcnt lgkmcnt(2)
	global_store_dwordx4 v129, v[88:91], s[26:27] nt
	s_waitcnt lgkmcnt(1)
	global_store_dwordx4 v130, v[92:95], s[26:27] nt
	s_waitcnt lgkmcnt(0)
	global_store_dwordx4 v131, v[96:99], s[26:27] nt
